# grid barrier: overall-last arriver publishes all per-XCD generation words (relay hop removed), others poll their per-XCD word
# speedup vs baseline: 1.0015x; 1.0015x over previous
.LBB0_160:
	s_or_b64 exec, exec, s[6:7]
	s_and_saveexec_b64 s[6:7], s[10:11]
	s_cbranch_execz .LBB0_162
	v_mov_b32_e32 v1, 1
	global_atomic_add v[2:3], v1, off
	v_mov_b32_e32 v230, 0x2400
	global_atomic_add v230, v1, s[88:89]
	v_add_u32_e32 v230, 0x100, v230
	global_atomic_add v230, v1, s[88:89]
	v_add_u32_e32 v230, 0x100, v230
	global_atomic_add v230, v1, s[88:89]
	v_add_u32_e32 v230, 0x100, v230
	global_atomic_add v230, v1, s[88:89]
	v_add_u32_e32 v230, 0x100, v230
	global_atomic_add v230, v1, s[88:89]
	v_add_u32_e32 v230, 0x100, v230
	global_atomic_add v230, v1, s[88:89]
	v_add_u32_e32 v230, 0x100, v230
	global_atomic_add v230, v1, s[88:89]
	v_add_u32_e32 v230, 0x100, v230
	global_atomic_add v230, v1, s[88:89]
	v_add_u32_e32 v230, 0x100, v230
	global_atomic_add v230, v1, s[88:89]
	v_add_u32_e32 v230, 0x100, v230
	global_atomic_add v230, v1, s[88:89]
	v_add_u32_e32 v230, 0x100, v230
	global_atomic_add v230, v1, s[88:89]
	v_add_u32_e32 v230, 0x100, v230
	global_atomic_add v230, v1, s[88:89]
	v_add_u32_e32 v230, 0x100, v230
	global_atomic_add v230, v1, s[88:89]
	v_add_u32_e32 v230, 0x100, v230
	global_atomic_add v230, v1, s[88:89]
	v_add_u32_e32 v230, 0x100, v230
	global_atomic_add v230, v1, s[88:89]
	v_add_u32_e32 v230, 0x100, v230
	global_atomic_add v230, v1, s[88:89]

.LBB0_221:
	s_or_b64 exec, exec, s[6:7]
	s_and_saveexec_b64 s[6:7], s[10:11]
	s_cbranch_execz .LBB0_223
	v_mov_b32_e32 v4, 1
	global_atomic_add v[2:3], v4, off
	v_mov_b32_e32 v230, 0x2400
	global_atomic_add v230, v4, s[88:89]
	v_add_u32_e32 v230, 0x100, v230
	global_atomic_add v230, v4, s[88:89]
	v_add_u32_e32 v230, 0x100, v230
	global_atomic_add v230, v4, s[88:89]
	v_add_u32_e32 v230, 0x100, v230
	global_atomic_add v230, v4, s[88:89]
	v_add_u32_e32 v230, 0x100, v230
	global_atomic_add v230, v4, s[88:89]
	v_add_u32_e32 v230, 0x100, v230
	global_atomic_add v230, v4, s[88:89]
	v_add_u32_e32 v230, 0x100, v230
	global_atomic_add v230, v4, s[88:89]
	v_add_u32_e32 v230, 0x100, v230
	global_atomic_add v230, v4, s[88:89]
	v_add_u32_e32 v230, 0x100, v230
	global_atomic_add v230, v4, s[88:89]
	v_add_u32_e32 v230, 0x100, v230
	global_atomic_add v230, v4, s[88:89]
	v_add_u32_e32 v230, 0x100, v230
	global_atomic_add v230, v4, s[88:89]
	v_add_u32_e32 v230, 0x100, v230
	global_atomic_add v230, v4, s[88:89]
	v_add_u32_e32 v230, 0x100, v230
	global_atomic_add v230, v4, s[88:89]
	v_add_u32_e32 v230, 0x100, v230
	global_atomic_add v230, v4, s[88:89]
	v_add_u32_e32 v230, 0x100, v230
	global_atomic_add v230, v4, s[88:89]
	v_add_u32_e32 v230, 0x100, v230
	global_atomic_add v230, v4, s[88:89]

.LBB0_474:
	s_or_b64 exec, exec, s[4:5]
	s_and_saveexec_b64 s[4:5], s[8:9]
	s_cbranch_execz .LBB0_476
	v_mov_b32_e32 v4, 1
	global_atomic_add v[2:3], v4, off
	v_mov_b32_e32 v230, 0x2400
	global_atomic_add v230, v4, s[88:89]
	v_add_u32_e32 v230, 0x100, v230
	global_atomic_add v230, v4, s[88:89]
	v_add_u32_e32 v230, 0x100, v230
	global_atomic_add v230, v4, s[88:89]
	v_add_u32_e32 v230, 0x100, v230
	global_atomic_add v230, v4, s[88:89]
	v_add_u32_e32 v230, 0x100, v230
	global_atomic_add v230, v4, s[88:89]
	v_add_u32_e32 v230, 0x100, v230
	global_atomic_add v230, v4, s[88:89]
	v_add_u32_e32 v230, 0x100, v230
	global_atomic_add v230, v4, s[88:89]
	v_add_u32_e32 v230, 0x100, v230
	global_atomic_add v230, v4, s[88:89]
	v_add_u32_e32 v230, 0x100, v230
	global_atomic_add v230, v4, s[88:89]
	v_add_u32_e32 v230, 0x100, v230
	global_atomic_add v230, v4, s[88:89]
	v_add_u32_e32 v230, 0x100, v230
	global_atomic_add v230, v4, s[88:89]
	v_add_u32_e32 v230, 0x100, v230
	global_atomic_add v230, v4, s[88:89]
	v_add_u32_e32 v230, 0x100, v230
	global_atomic_add v230, v4, s[88:89]
	v_add_u32_e32 v230, 0x100, v230
	global_atomic_add v230, v4, s[88:89]
	v_add_u32_e32 v230, 0x100, v230
	global_atomic_add v230, v4, s[88:89]
	v_add_u32_e32 v230, 0x100, v230
	global_atomic_add v230, v4, s[88:89]
